# stack + peeled first K-iteration with srcC=0 (accumulator zeroing v_movs removed) in G1 and G4
# speedup vs baseline: 1.0129x; 1.0008x over previous
;     __host__ __device__ bool next(int i, Unit& u) const { const int t = i / 3, b = i - 3 * t; Unit v; if (!StaticOrder::next(t, v)) return false; u.pm = v.pm; u.pn = 8 * b + v.pn; return true; }
; #define PG8_STAGE(bufoff, gbase, voff) do { const int so_ = (int)(unsigned)((const char*)(gbase) - base_##voff); _Pragma("unroll") for (int _i = 0; _i < 2; ++_i) \
;         __builtin_amdgcn_raw_ptr_buffer_load_lds(rs_##voff, (PG8_LAS unsigned*)(lds + (bufoff) + ldsw + _i * 8192), 16, (int)(voff)[_i], so_, 0, 0); } while (0)
; #define PG8_LDA(dst, b, h) do { _Pragma("unroll") for (int m = 0; m < 4; ++m) _Pragma("unroll") for (int k = 0; k < 2; ++k) dst[m][k] = *(const PG8_LAS bf16x8*)(lds + PG8_SA(b, h) + aoff + m * 2048 + k * 1024); } while (0)
; #define PG8_WAIT_V(n) asm volatile("s_waitcnt vmcnt(" #n ")" ::: "memory")
; #define PG8_WAIT_L(n) asm volatile("s_waitcnt lgkmcnt(" #n ")" ::: "memory")
; #define PG8_BAR __builtin_amdgcn_s_barrier()
; template <class Epi, class Sched, bool ALIGN_EPI = false, bool SP2 = false>
; __device__ __forceinline__ void gemm_phase(PG8_LAS unsigned char* lds, const Gemm g, const Sched& S, const Epi& E, int tid_in) {
;     ...
;         const bool has_next = S.next(ui + 1, nxt);
;         const char* nA = has_next ? (const char*)g.A + (size_t)nxt.pm * tstepA + (g.grp ? (size_t)(nxt.pn / g.grp) * g.agrp : (size_t)0) : cA; const char* nB = has_next ? (const char*)g.Bt + (size_t)nxt.pn * tstepB : cB;
;         for (int t = 0; t < nt; t += 2) {
;             const bool last = (t == nt - 2);
;             const char* a1 = cA + (size_t)(t + 1) * kstep;
;             const char* a2 = last ? nA : cA + (size_t)(t + 2) * kstep; const char* b2 = last ? nB : cB + (size_t)(t + 2) * kstep;
;             const char* a3 = a2 + kstep; const char* b3 = b2 + kstep;
;             if (last && has_next) S.a_ready(nxt);
;             if constexpr (SP2) {
;             PG8_LDB(B0, 0, 0); PG8_LDB(B1, 0, 1); PG8_SCHED; PG8_LDA(At, 0, 0); PG8_STAGE(PG8_SA(1, 1), a1 + hstepA, voffA);
;             PG8_WAIT_V(8); PG8_WAIT_L(0); PG8_BAR; PG8_MMA(0, 0, At, B0); PG8_MMA(0, 1, At, B1); PG8_BAR; PG8_SCHED;
;             PG8_LDA(At, 0, 1); PG8_STAGE(PG8_SB(0, 0), b2, voffB); PG8_STAGE(PG8_SB(0, 1), b2 + hstepB, voffB); PG8_STAGE(PG8_SA(0, 0), a2, voffA);
;             PG8_WAIT_V(8); PG8_WAIT_L(0); PG8_BAR; PG8_MMA(1, 0, At, B0); PG8_MMA(1, 1, At, B1); PG8_BAR; PG8_SCHED;
.LBB0_311:
	s_ashr_i32 s23, s22, 31
	s_lshl_b64 s[10:11], s[22:23], 20
	s_add_u32 s24, s4, s10
	s_addc_u32 s25, s26, s11
	s_and_b64 s[10:11], s[34:35], exec
	s_cselect_b32 s19, s24, s12
	s_ashr_i32 s15, s14, 31
	s_lshl_b64 s[10:11], s[14:15], 20
	s_add_u32 s10, s40, s10
	s_addc_u32 s11, s60, s11
	s_and_b64 s[20:21], s[34:35], exec
	s_cselect_b32 s15, s10, s16
	s_add_u32 s20, s16, 0x100
	v_mov_b32_e32 v2, 0
	s_addc_u32 s21, s17, 0
	s_mov_b32 s23, -2
	v_add_u32_e32 v0, 0x10000, v237
	ds_read_b128 v[130:133], v0
	ds_read_b128 v[134:137], v0 offset:1024
	ds_read_b128 v[138:141], v0 offset:2048
	ds_read_b128 v[142:145], v0 offset:3072
	v_add_u32_e32 v0, 0x14000, v237
	ds_read_b128 v[146:149], v0
	ds_read_b128 v[150:153], v0 offset:1024
	ds_read_b128 v[154:157], v0 offset:2048
	ds_read_b128 v[158:161], v0 offset:3072
	s_add_u32 s16, s12, 0x100
	s_addc_u32 s17, s13, 0
	s_sub_i32 s12, s12, s4
	s_add_i32 s12, s12, 0x80080
	s_sub_i32 s36, s12, 0x80000
	s_cmp_eq_u32 s23, 28
	s_cselect_b32 s13, s19, s16
	s_mov_b32 m0, s69
	ds_read_b128 v[162:165], v238
	ds_read_b128 v[166:169], v238 offset:1024
	ds_read_b128 v[170:173], v238 offset:2048
	ds_read_b128 v[174:177], v238 offset:3072
	ds_read_b128 v[178:181], v238 offset:4096
	ds_read_b128 v[182:185], v238 offset:5120
	ds_read_b128 v[186:189], v238 offset:6144
	ds_read_b128 v[190:193], v238 offset:7168
	s_mov_b32 m0, s78
	s_nop 0
	buffer_load_dwordx4 v211, s[4:7], s36 offen lds
	s_mov_b32 m0, s69
	s_nop 0
	buffer_load_dwordx4 v195, s[4:7], s12 offen lds
	s_mov_b32 m0, s67
	s_nop 0
	buffer_load_dwordx4 v211, s[4:7], s12 offen lds
	s_waitcnt vmcnt(8)
	s_waitcnt lgkmcnt(0)
	s_barrier
	s_setprio 1
	v_mfma_f32_16x16x32_bf16 v[126:129], v[130:133], v[162:165], 0
	v_mfma_f32_16x16x32_bf16 v[122:125], v[138:141], v[162:165], 0
	v_mfma_f32_16x16x32_bf16 v[106:109], v[138:141], v[170:173], 0
	v_mfma_f32_16x16x32_bf16 v[110:113], v[130:133], v[170:173], 0
	v_mfma_f32_16x16x32_bf16 v[94:97], v[130:133], v[178:181], 0
	v_mfma_f32_16x16x32_bf16 v[90:93], v[138:141], v[178:181], 0
	v_mfma_f32_16x16x32_bf16 v[74:77], v[138:141], v[186:189], 0
	v_mfma_f32_16x16x32_bf16 v[78:81], v[130:133], v[186:189], 0
	v_mfma_f32_16x16x32_bf16 v[126:129], v[134:137], v[166:169], v[126:129]
	v_mfma_f32_16x16x32_bf16 v[122:125], v[142:145], v[166:169], v[122:125]
	v_mfma_f32_16x16x32_bf16 v[106:109], v[142:145], v[174:177], v[106:109]
	v_mfma_f32_16x16x32_bf16 v[110:113], v[134:137], v[174:177], v[110:113]
	v_mfma_f32_16x16x32_bf16 v[94:97], v[134:137], v[182:185], v[94:97]
	v_mfma_f32_16x16x32_bf16 v[90:93], v[142:145], v[182:185], v[90:93]
	v_mfma_f32_16x16x32_bf16 v[74:77], v[142:145], v[190:193], v[74:77]
	v_mfma_f32_16x16x32_bf16 v[78:81], v[134:137], v[190:193], v[78:81]
	v_mfma_f32_16x16x32_bf16 v[118:121], v[146:149], v[162:165], 0
	v_mfma_f32_16x16x32_bf16 v[114:117], v[154:157], v[162:165], 0
	v_mfma_f32_16x16x32_bf16 v[98:101], v[154:157], v[170:173], 0
	v_mfma_f32_16x16x32_bf16 v[102:105], v[146:149], v[170:173], 0
	v_mfma_f32_16x16x32_bf16 v[86:89], v[146:149], v[178:181], 0
	v_mfma_f32_16x16x32_bf16 v[82:85], v[154:157], v[178:181], 0
	v_mfma_f32_16x16x32_bf16 v[66:69], v[154:157], v[186:189], 0
	v_mfma_f32_16x16x32_bf16 v[70:73], v[146:149], v[186:189], 0
	v_mfma_f32_16x16x32_bf16 v[118:121], v[150:153], v[166:169], v[118:121]
	v_mfma_f32_16x16x32_bf16 v[114:117], v[158:161], v[166:169], v[114:117]
	v_mfma_f32_16x16x32_bf16 v[98:101], v[158:161], v[174:177], v[98:101]
	v_mfma_f32_16x16x32_bf16 v[102:105], v[150:153], v[174:177], v[102:105]
	v_mfma_f32_16x16x32_bf16 v[86:89], v[150:153], v[182:185], v[86:89]
	v_mfma_f32_16x16x32_bf16 v[82:85], v[158:161], v[182:185], v[82:85]
	v_mfma_f32_16x16x32_bf16 v[66:69], v[158:161], v[190:193], v[66:69]
	v_mfma_f32_16x16x32_bf16 v[70:73], v[150:153], v[190:193], v[70:73]
	s_setprio 0
	s_barrier
	s_cselect_b32 s12, s15, s20
	s_mov_b32 m0, s61
	s_mov_b32 s42, s6
	s_mov_b32 s43, s7
	s_sub_i32 s12, s12, s40
	ds_read_b128 v[162:165], v238 offset:16384
	ds_read_b128 v[166:169], v238 offset:17408
	ds_read_b128 v[170:173], v238 offset:18432
	ds_read_b128 v[174:177], v238 offset:19456
	ds_read_b128 v[178:181], v238 offset:20480
	ds_read_b128 v[182:185], v238 offset:21504
	ds_read_b128 v[186:189], v238 offset:22528
	ds_read_b128 v[190:193], v238 offset:23552
	buffer_load_dwordx4 v207, s[40:43], s12 offen lds
	s_mov_b32 m0, s62
	s_add_i32 s36, s12, 0x80000
	buffer_load_dwordx4 v224, s[40:43], s12 offen lds
	s_mov_b32 m0, s63
	s_sub_i32 s13, s13, s4
	buffer_load_dwordx4 v207, s[40:43], s36 offen lds
	s_mov_b32 m0, s71
	s_nop 0
	buffer_load_dwordx4 v224, s[40:43], s36 offen lds
	s_mov_b32 m0, s53
	s_nop 0
	buffer_load_dwordx4 v195, s[4:7], s13 offen lds
	s_waitcnt vmcnt(7)
	s_waitcnt lgkmcnt(0)
	s_barrier
; #define PG8_STAGE(bufoff, gbase, voff) do { const int so_ = (int)(unsigned)((const char*)(gbase) - base_##voff); _Pragma("unroll") for (int _i = 0; _i < 2; ++_i) \
;         __builtin_amdgcn_raw_ptr_buffer_load_lds(rs_##voff, (PG8_LAS unsigned*)(lds + (bufoff) + ldsw + _i * 8192), 16, (int)(voff)[_i], so_, 0, 0); } while (0)
; #define PG8_LDA(dst, b, h) do { _Pragma("unroll") for (int m = 0; m < 4; ++m) _Pragma("unroll") for (int k = 0; k < 2; ++k) dst[m][k] = *(const PG8_LAS bf16x8*)(lds + PG8_SA(b, h) + aoff + m * 2048 + k * 1024); } while (0)
; #define PG8_LDB(dst, b, h) do { _Pragma("unroll") for (int n = 0; n < 2; ++n) _Pragma("unroll") for (int k = 0; k < 2; ++k) dst[n][k] = *(const PG8_LAS bf16x8*)(lds + PG8_SB(b, h) + boff + n * 2048 + k * 1024); } while (0)
; #define PG8_MMA(ai, bj, At, Bt) do { __builtin_amdgcn_s_setprio(1); _Pragma("unroll") for (int m = 0; m < 4; ++m) _Pragma("unroll") for (int n = 0; n < 2; ++n) _Pragma("unroll") for (int k = 0; k < 2; ++k) \
;         acc[ai][bj][m][n] = __builtin_amdgcn_mfma_f32_16x16x32_bf16(Bt[n][k], At[m][k], acc[ai][bj][m][n], 0, 0, 0); __builtin_amdgcn_s_setprio(0); } while (0)
; #define PG8_WAIT_V(n) asm volatile("s_waitcnt vmcnt(" #n ")" ::: "memory")
; #define PG8_WAIT_L(n) asm volatile("s_waitcnt lgkmcnt(" #n ")" ::: "memory")
; #define PG8_BAR __builtin_amdgcn_s_barrier()
; #define PG8_SCHED __builtin_amdgcn_sched_barrier(0)
; template <class Epi, class Sched, bool ALIGN_EPI = false, bool SP2 = false>
; __device__ __forceinline__ void gemm_phase(PG8_LAS unsigned char* lds, const Gemm g, const Sched& S, const Epi& E, int tid_in) {
;     ...
;             PG8_WAIT_V(8); PG8_WAIT_L(0); PG8_BAR; PG8_MMA(1, 0, At, B0); PG8_MMA(1, 1, At, B1); PG8_BAR; PG8_SCHED;
;             PG8_LDB(B0, 1, 0); PG8_LDB(B1, 1, 1); PG8_SCHED; PG8_LDA(At, 1, 0); PG8_STAGE(PG8_SA(0, 1), a2 + hstepA, voffA);
;             PG8_WAIT_V(8); PG8_WAIT_L(0); PG8_BAR; PG8_MMA(0, 0, At, B0); PG8_MMA(0, 1, At, B1); PG8_BAR; PG8_SCHED;
	s_setprio 1
	v_mfma_f32_16x16x32_bf16 v[62:65], v[130:133], v[162:165], 0
	v_mfma_f32_16x16x32_bf16 v[58:61], v[138:141], v[162:165], 0
	v_mfma_f32_16x16x32_bf16 v[42:45], v[138:141], v[170:173], 0
	v_mfma_f32_16x16x32_bf16 v[46:49], v[130:133], v[170:173], 0
	v_mfma_f32_16x16x32_bf16 v[30:33], v[130:133], v[178:181], 0
	v_mfma_f32_16x16x32_bf16 v[26:29], v[138:141], v[178:181], 0
	v_mfma_f32_16x16x32_bf16 v[10:13], v[138:141], v[186:189], 0
	v_mfma_f32_16x16x32_bf16 v[14:17], v[130:133], v[186:189], 0
	v_mfma_f32_16x16x32_bf16 v[62:65], v[134:137], v[166:169], v[62:65]
	v_mfma_f32_16x16x32_bf16 v[58:61], v[142:145], v[166:169], v[58:61]
	v_mfma_f32_16x16x32_bf16 v[42:45], v[142:145], v[174:177], v[42:45]
	v_mfma_f32_16x16x32_bf16 v[46:49], v[134:137], v[174:177], v[46:49]
	v_mfma_f32_16x16x32_bf16 v[30:33], v[134:137], v[182:185], v[30:33]
	v_mfma_f32_16x16x32_bf16 v[26:29], v[142:145], v[182:185], v[26:29]
	v_mfma_f32_16x16x32_bf16 v[10:13], v[142:145], v[190:193], v[10:13]
	v_mfma_f32_16x16x32_bf16 v[14:17], v[134:137], v[190:193], v[14:17]
	v_mfma_f32_16x16x32_bf16 v[54:57], v[146:149], v[162:165], 0
	v_mfma_f32_16x16x32_bf16 v[50:53], v[154:157], v[162:165], 0
	v_mfma_f32_16x16x32_bf16 v[34:37], v[154:157], v[170:173], 0
	v_mfma_f32_16x16x32_bf16 v[38:41], v[146:149], v[170:173], 0
	v_mfma_f32_16x16x32_bf16 v[22:25], v[146:149], v[178:181], 0
	v_mfma_f32_16x16x32_bf16 v[18:21], v[154:157], v[178:181], 0
	v_mfma_f32_16x16x32_bf16 v[2:5], v[154:157], v[186:189], 0
	v_mfma_f32_16x16x32_bf16 v[6:9], v[146:149], v[186:189], 0
	v_mfma_f32_16x16x32_bf16 v[54:57], v[150:153], v[166:169], v[54:57]
	v_mfma_f32_16x16x32_bf16 v[50:53], v[158:161], v[166:169], v[50:53]
	v_mfma_f32_16x16x32_bf16 v[34:37], v[158:161], v[174:177], v[34:37]
	v_mfma_f32_16x16x32_bf16 v[38:41], v[150:153], v[174:177], v[38:41]
	v_mfma_f32_16x16x32_bf16 v[22:25], v[150:153], v[182:185], v[22:25]
	v_mfma_f32_16x16x32_bf16 v[18:21], v[158:161], v[182:185], v[18:21]
	v_mfma_f32_16x16x32_bf16 v[2:5], v[158:161], v[190:193], v[2:5]
	v_mfma_f32_16x16x32_bf16 v[6:9], v[150:153], v[190:193], v[6:9]
	s_setprio 0
	s_barrier
	v_add_u32_e32 v0, 0x18000, v237
	ds_read_b128 v[130:133], v0
	ds_read_b128 v[134:137], v0 offset:1024
	ds_read_b128 v[138:141], v0 offset:2048
	ds_read_b128 v[142:145], v0 offset:3072
	v_add_u32_e32 v0, 0x1c000, v237
	ds_read_b128 v[146:149], v0
	ds_read_b128 v[150:153], v0 offset:1024
	ds_read_b128 v[154:157], v0 offset:2048
	ds_read_b128 v[158:161], v0 offset:3072
	s_add_i32 s36, s13, 0x80000
	s_mov_b32 m0, s73
	ds_read_b128 v[162:165], v238 offset:32768
	ds_read_b128 v[166:169], v238 offset:33792
	ds_read_b128 v[170:173], v238 offset:34816
	ds_read_b128 v[174:177], v238 offset:35840
	ds_read_b128 v[178:181], v238 offset:36864
	ds_read_b128 v[182:185], v238 offset:37888
	ds_read_b128 v[186:189], v238 offset:38912
	ds_read_b128 v[190:193], v238 offset:39936
	s_mov_b32 m0, s72
	s_nop 0
	buffer_load_dwordx4 v211, s[4:7], s13 offen lds
	s_mov_b32 m0, s73
	s_nop 0
	buffer_load_dwordx4 v195, s[4:7], s36 offen lds
	s_mov_b32 m0, s74
	s_nop 0
	buffer_load_dwordx4 v211, s[4:7], s36 offen lds
	s_waitcnt vmcnt(8)
	s_waitcnt lgkmcnt(0)
	s_barrier
	s_setprio 1
	v_mfma_f32_16x16x32_bf16 v[126:129], v[130:133], v[162:165], v[126:129]
	v_mfma_f32_16x16x32_bf16 v[122:125], v[138:141], v[162:165], v[122:125]
	v_mfma_f32_16x16x32_bf16 v[106:109], v[138:141], v[170:173], v[106:109]
	v_mfma_f32_16x16x32_bf16 v[110:113], v[130:133], v[170:173], v[110:113]
	v_mfma_f32_16x16x32_bf16 v[94:97], v[130:133], v[178:181], v[94:97]
	v_mfma_f32_16x16x32_bf16 v[90:93], v[138:141], v[178:181], v[90:93]
	v_mfma_f32_16x16x32_bf16 v[74:77], v[138:141], v[186:189], v[74:77]
	v_mfma_f32_16x16x32_bf16 v[78:81], v[130:133], v[186:189], v[78:81]
	v_mfma_f32_16x16x32_bf16 v[126:129], v[134:137], v[166:169], v[126:129]
	v_mfma_f32_16x16x32_bf16 v[122:125], v[142:145], v[166:169], v[122:125]
	v_mfma_f32_16x16x32_bf16 v[106:109], v[142:145], v[174:177], v[106:109]
	v_mfma_f32_16x16x32_bf16 v[110:113], v[134:137], v[174:177], v[110:113]
	v_mfma_f32_16x16x32_bf16 v[94:97], v[134:137], v[182:185], v[94:97]
	v_mfma_f32_16x16x32_bf16 v[90:93], v[142:145], v[182:185], v[90:93]
	v_mfma_f32_16x16x32_bf16 v[74:77], v[142:145], v[190:193], v[74:77]
	v_mfma_f32_16x16x32_bf16 v[78:81], v[134:137], v[190:193], v[78:81]
	v_mfma_f32_16x16x32_bf16 v[118:121], v[146:149], v[162:165], v[118:121]
	v_mfma_f32_16x16x32_bf16 v[114:117], v[154:157], v[162:165], v[114:117]
	v_mfma_f32_16x16x32_bf16 v[98:101], v[154:157], v[170:173], v[98:101]
	v_mfma_f32_16x16x32_bf16 v[102:105], v[146:149], v[170:173], v[102:105]
	v_mfma_f32_16x16x32_bf16 v[86:89], v[146:149], v[178:181], v[86:89]
	v_mfma_f32_16x16x32_bf16 v[82:85], v[154:157], v[178:181], v[82:85]
	v_mfma_f32_16x16x32_bf16 v[66:69], v[154:157], v[186:189], v[66:69]
	v_mfma_f32_16x16x32_bf16 v[70:73], v[146:149], v[186:189], v[70:73]
	v_mfma_f32_16x16x32_bf16 v[118:121], v[150:153], v[166:169], v[118:121]
	v_mfma_f32_16x16x32_bf16 v[114:117], v[158:161], v[166:169], v[114:117]
	v_mfma_f32_16x16x32_bf16 v[98:101], v[158:161], v[174:177], v[98:101]
	v_mfma_f32_16x16x32_bf16 v[102:105], v[150:153], v[174:177], v[102:105]
	v_mfma_f32_16x16x32_bf16 v[86:89], v[150:153], v[182:185], v[86:89]
	v_mfma_f32_16x16x32_bf16 v[82:85], v[158:161], v[182:185], v[82:85]
	v_mfma_f32_16x16x32_bf16 v[66:69], v[158:161], v[190:193], v[66:69]
	v_mfma_f32_16x16x32_bf16 v[70:73], v[150:153], v[190:193], v[70:73]
	s_setprio 0
	s_barrier
; #define PG8_STAGE(bufoff, gbase, voff) do { const int so_ = (int)(unsigned)((const char*)(gbase) - base_##voff); _Pragma("unroll") for (int _i = 0; _i < 2; ++_i) \
;         __builtin_amdgcn_raw_ptr_buffer_load_lds(rs_##voff, (PG8_LAS unsigned*)(lds + (bufoff) + ldsw + _i * 8192), 16, (int)(voff)[_i], so_, 0, 0); } while (0)
; #define PG8_LDA(dst, b, h) do { _Pragma("unroll") for (int m = 0; m < 4; ++m) _Pragma("unroll") for (int k = 0; k < 2; ++k) dst[m][k] = *(const PG8_LAS bf16x8*)(lds + PG8_SA(b, h) + aoff + m * 2048 + k * 1024); } while (0)
; #define PG8_MMA(ai, bj, At, Bt) do { __builtin_amdgcn_s_setprio(1); _Pragma("unroll") for (int m = 0; m < 4; ++m) _Pragma("unroll") for (int n = 0; n < 2; ++n) _Pragma("unroll") for (int k = 0; k < 2; ++k) \
;         acc[ai][bj][m][n] = __builtin_amdgcn_mfma_f32_16x16x32_bf16(Bt[n][k], At[m][k], acc[ai][bj][m][n], 0, 0, 0); __builtin_amdgcn_s_setprio(0); } while (0)
; #define PG8_WAIT_V(n) asm volatile("s_waitcnt vmcnt(" #n ")" ::: "memory")
; #define PG8_WAIT_L(n) asm volatile("s_waitcnt lgkmcnt(" #n ")" ::: "memory")
; #define PG8_BAR __builtin_amdgcn_s_barrier()
; #define PG8_SCHED __builtin_amdgcn_sched_barrier(0)
; template <class Epi, class Sched, bool ALIGN_EPI = false, bool SP2 = false>
; __device__ __forceinline__ void gemm_phase(PG8_LAS unsigned char* lds, const Gemm g, const Sched& S, const Epi& E, int tid_in) {
;     ...
;         for (int t = 0; t < nt; t += 2) {
;     ...
;             PG8_LDA(At, 1, 1); PG8_STAGE(PG8_SB(1, 0), b3, voffB); PG8_STAGE(PG8_SB(1, 1), b3 + hstepB, voffB); PG8_STAGE(PG8_SA(1, 0), a3, voffA);
;             PG8_WAIT_V(8); PG8_WAIT_L(0); PG8_BAR; PG8_MMA(1, 0, At, B0); PG8_MMA(1, 1, At, B1); PG8_BAR; PG8_SCHED;
	s_mov_b32 m0, s75
	s_add_i32 s36, s12, 0x80
	ds_read_b128 v[162:165], v238 offset:49152
	ds_read_b128 v[166:169], v238 offset:50176
	ds_read_b128 v[170:173], v238 offset:51200
	ds_read_b128 v[174:177], v238 offset:52224
	ds_read_b128 v[178:181], v238 offset:53248
	ds_read_b128 v[182:185], v238 offset:54272
	ds_read_b128 v[186:189], v238 offset:55296
	ds_read_b128 v[190:193], v238 offset:56320
	buffer_load_dwordx4 v207, s[40:43], s36 offen lds
	s_mov_b32 m0, s76
	s_add_i32 s12, s12, 0x80080
	buffer_load_dwordx4 v224, s[40:43], s36 offen lds
	s_mov_b32 m0, s79
	s_addk_i32 s13, 0x80
	buffer_load_dwordx4 v207, s[40:43], s12 offen lds
	s_mov_b32 m0, s68
	s_nop 0
	buffer_load_dwordx4 v224, s[40:43], s12 offen lds
	s_mov_b32 m0, s77
	s_nop 0
	buffer_load_dwordx4 v195, s[4:7], s13 offen lds
	s_waitcnt vmcnt(7)
	s_waitcnt lgkmcnt(0)
	s_barrier
	s_setprio 1
	v_mfma_f32_16x16x32_bf16 v[62:65], v[130:133], v[162:165], v[62:65]
	v_mfma_f32_16x16x32_bf16 v[58:61], v[138:141], v[162:165], v[58:61]
	v_mfma_f32_16x16x32_bf16 v[42:45], v[138:141], v[170:173], v[42:45]
	v_mfma_f32_16x16x32_bf16 v[46:49], v[130:133], v[170:173], v[46:49]
	v_mfma_f32_16x16x32_bf16 v[30:33], v[130:133], v[178:181], v[30:33]
	v_mfma_f32_16x16x32_bf16 v[26:29], v[138:141], v[178:181], v[26:29]
	v_mfma_f32_16x16x32_bf16 v[10:13], v[138:141], v[186:189], v[10:13]
	v_mfma_f32_16x16x32_bf16 v[14:17], v[130:133], v[186:189], v[14:17]
	v_mfma_f32_16x16x32_bf16 v[62:65], v[134:137], v[166:169], v[62:65]
	v_mfma_f32_16x16x32_bf16 v[58:61], v[142:145], v[166:169], v[58:61]
	v_mfma_f32_16x16x32_bf16 v[42:45], v[142:145], v[174:177], v[42:45]
	v_mfma_f32_16x16x32_bf16 v[46:49], v[134:137], v[174:177], v[46:49]
	v_mfma_f32_16x16x32_bf16 v[30:33], v[134:137], v[182:185], v[30:33]
	v_mfma_f32_16x16x32_bf16 v[26:29], v[142:145], v[182:185], v[26:29]
	v_mfma_f32_16x16x32_bf16 v[10:13], v[142:145], v[190:193], v[10:13]
	v_mfma_f32_16x16x32_bf16 v[14:17], v[134:137], v[190:193], v[14:17]
	v_mfma_f32_16x16x32_bf16 v[54:57], v[146:149], v[162:165], v[54:57]
	v_mfma_f32_16x16x32_bf16 v[50:53], v[154:157], v[162:165], v[50:53]
	v_mfma_f32_16x16x32_bf16 v[34:37], v[154:157], v[170:173], v[34:37]
	v_mfma_f32_16x16x32_bf16 v[38:41], v[146:149], v[170:173], v[38:41]
	v_mfma_f32_16x16x32_bf16 v[22:25], v[146:149], v[178:181], v[22:25]
	v_mfma_f32_16x16x32_bf16 v[18:21], v[154:157], v[178:181], v[18:21]
	v_mfma_f32_16x16x32_bf16 v[2:5], v[154:157], v[186:189], v[2:5]
	v_mfma_f32_16x16x32_bf16 v[6:9], v[146:149], v[186:189], v[6:9]
	v_mfma_f32_16x16x32_bf16 v[54:57], v[150:153], v[166:169], v[54:57]
	v_mfma_f32_16x16x32_bf16 v[50:53], v[158:161], v[166:169], v[50:53]
	v_mfma_f32_16x16x32_bf16 v[34:37], v[158:161], v[174:177], v[34:37]
	v_mfma_f32_16x16x32_bf16 v[38:41], v[150:153], v[174:177], v[38:41]
	v_mfma_f32_16x16x32_bf16 v[22:25], v[150:153], v[182:185], v[22:25]
	v_mfma_f32_16x16x32_bf16 v[18:21], v[158:161], v[182:185], v[18:21]
	v_mfma_f32_16x16x32_bf16 v[2:5], v[158:161], v[190:193], v[2:5]
	v_mfma_f32_16x16x32_bf16 v[6:9], v[150:153], v[190:193], v[6:9]
	s_setprio 0
	s_barrier
	s_add_i32 s23, s23, 2
	s_add_u32 s20, s20, 0x100
	s_addc_u32 s21, s21, 0
	s_cmp_gt_u32 s23, 29
	s_mov_b64 s[12:13], s[16:17]

;     __host__ __device__ bool next(int i, Unit& u) const { const int t = i / 3, b = i - 3 * t; Unit v; if (!StaticOrder::next(t, v)) return false; u.pm = v.pm; u.pn = 8 * b + v.pn; return true; }
; #define PG8_STAGE(bufoff, gbase, voff) do { const int so_ = (int)(unsigned)((const char*)(gbase) - base_##voff); _Pragma("unroll") for (int _i = 0; _i < 2; ++_i) \
;         __builtin_amdgcn_raw_ptr_buffer_load_lds(rs_##voff, (PG8_LAS unsigned*)(lds + (bufoff) + ldsw + _i * 8192), 16, (int)(voff)[_i], so_, 0, 0); } while (0)
; #define PG8_LDA(dst, b, h) do { _Pragma("unroll") for (int m = 0; m < 4; ++m) _Pragma("unroll") for (int k = 0; k < 2; ++k) dst[m][k] = *(const PG8_LAS bf16x8*)(lds + PG8_SA(b, h) + aoff + m * 2048 + k * 1024); } while (0)
; #define PG8_WAIT_V(n) asm volatile("s_waitcnt vmcnt(" #n ")" ::: "memory")
; #define PG8_WAIT_L(n) asm volatile("s_waitcnt lgkmcnt(" #n ")" ::: "memory")
; #define PG8_BAR __builtin_amdgcn_s_barrier()
; template <class Epi, class Sched, bool ALIGN_EPI = false, bool SP2 = false>
; __device__ __forceinline__ void gemm_phase(PG8_LAS unsigned char* lds, const Gemm g, const Sched& S, const Epi& E, int tid_in) {
;     ...
;         const bool has_next = S.next(ui + 1, nxt);
;         const char* nA = has_next ? (const char*)g.A + (size_t)nxt.pm * tstepA + (g.grp ? (size_t)(nxt.pn / g.grp) * g.agrp : (size_t)0) : cA; const char* nB = has_next ? (const char*)g.Bt + (size_t)nxt.pn * tstepB : cB;
;         for (int t = 0; t < nt; t += 2) {
;             const bool last = (t == nt - 2);
;             const char* a1 = cA + (size_t)(t + 1) * kstep;
;             const char* a2 = last ? nA : cA + (size_t)(t + 2) * kstep; const char* b2 = last ? nB : cB + (size_t)(t + 2) * kstep;
;             const char* a3 = a2 + kstep; const char* b3 = b2 + kstep;
;             if (last && has_next) S.a_ready(nxt);
;             if constexpr (SP2) {
;             PG8_LDB(B0, 0, 0); PG8_LDB(B1, 0, 1); PG8_SCHED; PG8_LDA(At, 0, 0); PG8_STAGE(PG8_SA(1, 1), a1 + hstepA, voffA);
;             PG8_WAIT_V(8); PG8_WAIT_L(0); PG8_BAR; PG8_MMA(0, 0, At, B0); PG8_MMA(0, 1, At, B1); PG8_BAR; PG8_SCHED;
;             PG8_LDA(At, 0, 1); PG8_STAGE(PG8_SB(0, 0), b2, voffB); PG8_STAGE(PG8_SB(0, 1), b2 + hstepB, voffB); PG8_STAGE(PG8_SA(0, 0), a2, voffA);
;             PG8_WAIT_V(8); PG8_WAIT_L(0); PG8_BAR; PG8_MMA(1, 0, At, B0); PG8_MMA(1, 1, At, B1); PG8_BAR; PG8_SCHED;
.LBB0_1513:
	s_ashr_i32 s21, s20, 31
	s_lshl_b64 s[18:19], s[20:21], 20
	s_add_u32 s22, s4, s18
	s_addc_u32 s23, s9, s19
	s_and_b64 s[18:19], s[36:37], exec
	s_cselect_b32 s18, s22, s16
	s_ashr_i32 s15, s14, 31
	s_lshl_b64 s[24:25], s[14:15], 20
	s_add_u32 s24, s40, s24
	s_addc_u32 s25, s26, s25
	s_and_b64 s[42:43], s[36:37], exec
	s_cselect_b32 s15, s24, s38
	s_add_u32 s19, s38, 0x100
	v_mov_b32_e32 v2, 0
	s_addc_u32 s21, s39, 0
	s_mov_b32 s73, -2
	v_add_u32_e32 v141, 0x10000, v139
	ds_read_b128 v[130:133], v141
	ds_read_b128 v[142:145], v141 offset:1024
	ds_read_b128 v[146:149], v141 offset:2048
	ds_read_b128 v[150:153], v141 offset:3072
	v_add_u32_e32 v141, 0x14000, v139
	ds_read_b128 v[154:157], v141
	ds_read_b128 v[158:161], v141 offset:1024
	ds_read_b128 v[162:165], v141 offset:2048
	ds_read_b128 v[166:169], v141 offset:3072
	s_add_u32 s38, s16, 0x100
	s_addc_u32 s39, s17, 0
	s_sub_i32 s16, s16, s4
	s_add_i32 s16, s16, 0x80080
	s_sub_i32 s74, s16, 0x80000
	s_cmp_eq_u32 s73, 28
	s_cselect_b32 s17, s18, s38
	s_mov_b32 m0, s67
	ds_read_b128 v[170:173], v140
	ds_read_b128 v[174:177], v140 offset:1024
	ds_read_b128 v[178:181], v140 offset:2048
	ds_read_b128 v[182:185], v140 offset:3072
	ds_read_b128 v[186:189], v140 offset:4096
	ds_read_b128 v[190:193], v140 offset:5120
	ds_read_b128 v[200:203], v140 offset:6144
	ds_read_b128 v[206:209], v140 offset:7168
	s_mov_b32 m0, s62
	s_nop 0
	buffer_load_dwordx4 v135, s[4:7], s74 offen lds
	s_mov_b32 m0, s67
	s_nop 0
	buffer_load_dwordx4 v0, s[4:7], s16 offen lds
	s_mov_b32 m0, s68
	s_nop 0
	buffer_load_dwordx4 v135, s[4:7], s16 offen lds
	s_waitcnt vmcnt(8)
	s_waitcnt lgkmcnt(0)
	s_barrier
	s_setprio 1
	v_mfma_f32_16x16x32_bf16 v[126:129], v[130:133], v[170:173], 0
	v_mfma_f32_16x16x32_bf16 v[122:125], v[146:149], v[170:173], 0
	v_mfma_f32_16x16x32_bf16 v[106:109], v[146:149], v[178:181], 0
	v_mfma_f32_16x16x32_bf16 v[110:113], v[130:133], v[178:181], 0
	v_mfma_f32_16x16x32_bf16 v[94:97], v[130:133], v[186:189], 0
	v_mfma_f32_16x16x32_bf16 v[90:93], v[146:149], v[186:189], 0
	v_mfma_f32_16x16x32_bf16 v[74:77], v[146:149], v[200:203], 0
	v_mfma_f32_16x16x32_bf16 v[78:81], v[130:133], v[200:203], 0
	v_mfma_f32_16x16x32_bf16 v[126:129], v[142:145], v[174:177], v[126:129]
	v_mfma_f32_16x16x32_bf16 v[122:125], v[150:153], v[174:177], v[122:125]
	v_mfma_f32_16x16x32_bf16 v[106:109], v[150:153], v[182:185], v[106:109]
	v_mfma_f32_16x16x32_bf16 v[110:113], v[142:145], v[182:185], v[110:113]
	v_mfma_f32_16x16x32_bf16 v[94:97], v[142:145], v[190:193], v[94:97]
	v_mfma_f32_16x16x32_bf16 v[90:93], v[150:153], v[190:193], v[90:93]
	v_mfma_f32_16x16x32_bf16 v[74:77], v[150:153], v[206:209], v[74:77]
	v_mfma_f32_16x16x32_bf16 v[78:81], v[142:145], v[206:209], v[78:81]
	v_mfma_f32_16x16x32_bf16 v[118:121], v[154:157], v[170:173], 0
	v_mfma_f32_16x16x32_bf16 v[114:117], v[162:165], v[170:173], 0
	v_mfma_f32_16x16x32_bf16 v[98:101], v[162:165], v[178:181], 0
	v_mfma_f32_16x16x32_bf16 v[102:105], v[154:157], v[178:181], 0
	v_mfma_f32_16x16x32_bf16 v[86:89], v[154:157], v[186:189], 0
	v_mfma_f32_16x16x32_bf16 v[82:85], v[162:165], v[186:189], 0
	v_mfma_f32_16x16x32_bf16 v[66:69], v[162:165], v[200:203], 0
	v_mfma_f32_16x16x32_bf16 v[70:73], v[154:157], v[200:203], 0
	v_mfma_f32_16x16x32_bf16 v[118:121], v[158:161], v[174:177], v[118:121]
	v_mfma_f32_16x16x32_bf16 v[114:117], v[166:169], v[174:177], v[114:117]
	v_mfma_f32_16x16x32_bf16 v[98:101], v[166:169], v[182:185], v[98:101]
	v_mfma_f32_16x16x32_bf16 v[102:105], v[158:161], v[182:185], v[102:105]
	v_mfma_f32_16x16x32_bf16 v[86:89], v[158:161], v[190:193], v[86:89]
	v_mfma_f32_16x16x32_bf16 v[82:85], v[166:169], v[190:193], v[82:85]
	v_mfma_f32_16x16x32_bf16 v[66:69], v[166:169], v[206:209], v[66:69]
	v_mfma_f32_16x16x32_bf16 v[70:73], v[158:161], v[206:209], v[70:73]
	s_setprio 0
	s_barrier
	s_cselect_b32 s16, s15, s19
	s_mov_b32 m0, s35
	s_mov_b32 s42, s6
	s_mov_b32 s43, s7
	s_sub_i32 s16, s16, s40
	ds_read_b128 v[170:173], v140 offset:16384
	ds_read_b128 v[174:177], v140 offset:17408
	ds_read_b128 v[178:181], v140 offset:18432
	ds_read_b128 v[182:185], v140 offset:19456
	ds_read_b128 v[186:189], v140 offset:20480
	ds_read_b128 v[190:193], v140 offset:21504
	ds_read_b128 v[200:203], v140 offset:22528
	ds_read_b128 v[206:209], v140 offset:23552
	buffer_load_dwordx4 v134, s[40:43], s16 offen lds
	s_mov_b32 m0, s44
	s_add_i32 s74, s16, 0x80000
	buffer_load_dwordx4 v136, s[40:43], s16 offen lds
	s_mov_b32 m0, s45
	s_sub_i32 s17, s17, s4
	buffer_load_dwordx4 v134, s[40:43], s74 offen lds
	s_mov_b32 m0, s46
	s_nop 0
	buffer_load_dwordx4 v136, s[40:43], s74 offen lds
	s_mov_b32 m0, s34
	s_nop 0
	buffer_load_dwordx4 v0, s[4:7], s17 offen lds
	s_waitcnt vmcnt(7)
	s_waitcnt lgkmcnt(0)
	s_barrier
; #define PG8_STAGE(bufoff, gbase, voff) do { const int so_ = (int)(unsigned)((const char*)(gbase) - base_##voff); _Pragma("unroll") for (int _i = 0; _i < 2; ++_i) \
;         __builtin_amdgcn_raw_ptr_buffer_load_lds(rs_##voff, (PG8_LAS unsigned*)(lds + (bufoff) + ldsw + _i * 8192), 16, (int)(voff)[_i], so_, 0, 0); } while (0)
; #define PG8_LDA(dst, b, h) do { _Pragma("unroll") for (int m = 0; m < 4; ++m) _Pragma("unroll") for (int k = 0; k < 2; ++k) dst[m][k] = *(const PG8_LAS bf16x8*)(lds + PG8_SA(b, h) + aoff + m * 2048 + k * 1024); } while (0)
; #define PG8_LDB(dst, b, h) do { _Pragma("unroll") for (int n = 0; n < 2; ++n) _Pragma("unroll") for (int k = 0; k < 2; ++k) dst[n][k] = *(const PG8_LAS bf16x8*)(lds + PG8_SB(b, h) + boff + n * 2048 + k * 1024); } while (0)
; #define PG8_MMA(ai, bj, At, Bt) do { __builtin_amdgcn_s_setprio(1); _Pragma("unroll") for (int m = 0; m < 4; ++m) _Pragma("unroll") for (int n = 0; n < 2; ++n) _Pragma("unroll") for (int k = 0; k < 2; ++k) \
;         acc[ai][bj][m][n] = __builtin_amdgcn_mfma_f32_16x16x32_bf16(Bt[n][k], At[m][k], acc[ai][bj][m][n], 0, 0, 0); __builtin_amdgcn_s_setprio(0); } while (0)
; #define PG8_WAIT_V(n) asm volatile("s_waitcnt vmcnt(" #n ")" ::: "memory")
; #define PG8_WAIT_L(n) asm volatile("s_waitcnt lgkmcnt(" #n ")" ::: "memory")
; #define PG8_BAR __builtin_amdgcn_s_barrier()
; #define PG8_SCHED __builtin_amdgcn_sched_barrier(0)
; template <class Epi, class Sched, bool ALIGN_EPI = false, bool SP2 = false>
; __device__ __forceinline__ void gemm_phase(PG8_LAS unsigned char* lds, const Gemm g, const Sched& S, const Epi& E, int tid_in) {
;     ...
;             PG8_WAIT_V(8); PG8_WAIT_L(0); PG8_BAR; PG8_MMA(1, 0, At, B0); PG8_MMA(1, 1, At, B1); PG8_BAR; PG8_SCHED;
;             PG8_LDB(B0, 1, 0); PG8_LDB(B1, 1, 1); PG8_SCHED; PG8_LDA(At, 1, 0); PG8_STAGE(PG8_SA(0, 1), a2 + hstepA, voffA);
;             PG8_WAIT_V(8); PG8_WAIT_L(0); PG8_BAR; PG8_MMA(0, 0, At, B0); PG8_MMA(0, 1, At, B1); PG8_BAR; PG8_SCHED;
	s_setprio 1
	v_mfma_f32_16x16x32_bf16 v[62:65], v[130:133], v[170:173], 0
	v_mfma_f32_16x16x32_bf16 v[58:61], v[146:149], v[170:173], 0
	v_mfma_f32_16x16x32_bf16 v[42:45], v[146:149], v[178:181], 0
	v_mfma_f32_16x16x32_bf16 v[46:49], v[130:133], v[178:181], 0
	v_mfma_f32_16x16x32_bf16 v[30:33], v[130:133], v[186:189], 0
	v_mfma_f32_16x16x32_bf16 v[26:29], v[146:149], v[186:189], 0
	v_mfma_f32_16x16x32_bf16 v[10:13], v[146:149], v[200:203], 0
	v_mfma_f32_16x16x32_bf16 v[14:17], v[130:133], v[200:203], 0
	v_mfma_f32_16x16x32_bf16 v[62:65], v[142:145], v[174:177], v[62:65]
	v_mfma_f32_16x16x32_bf16 v[58:61], v[150:153], v[174:177], v[58:61]
	v_mfma_f32_16x16x32_bf16 v[42:45], v[150:153], v[182:185], v[42:45]
	v_mfma_f32_16x16x32_bf16 v[46:49], v[142:145], v[182:185], v[46:49]
	v_mfma_f32_16x16x32_bf16 v[30:33], v[142:145], v[190:193], v[30:33]
	v_mfma_f32_16x16x32_bf16 v[26:29], v[150:153], v[190:193], v[26:29]
	v_mfma_f32_16x16x32_bf16 v[10:13], v[150:153], v[206:209], v[10:13]
	v_mfma_f32_16x16x32_bf16 v[14:17], v[142:145], v[206:209], v[14:17]
	v_mfma_f32_16x16x32_bf16 v[54:57], v[154:157], v[170:173], 0
	v_mfma_f32_16x16x32_bf16 v[50:53], v[162:165], v[170:173], 0
	v_mfma_f32_16x16x32_bf16 v[34:37], v[162:165], v[178:181], 0
	v_mfma_f32_16x16x32_bf16 v[38:41], v[154:157], v[178:181], 0
	v_mfma_f32_16x16x32_bf16 v[22:25], v[154:157], v[186:189], 0
	v_mfma_f32_16x16x32_bf16 v[18:21], v[162:165], v[186:189], 0
	v_mfma_f32_16x16x32_bf16 v[2:5], v[162:165], v[200:203], 0
	v_mfma_f32_16x16x32_bf16 v[6:9], v[154:157], v[200:203], 0
	v_mfma_f32_16x16x32_bf16 v[54:57], v[158:161], v[174:177], v[54:57]
	v_mfma_f32_16x16x32_bf16 v[50:53], v[166:169], v[174:177], v[50:53]
	v_mfma_f32_16x16x32_bf16 v[34:37], v[166:169], v[182:185], v[34:37]
	v_mfma_f32_16x16x32_bf16 v[38:41], v[158:161], v[182:185], v[38:41]
	v_mfma_f32_16x16x32_bf16 v[22:25], v[158:161], v[190:193], v[22:25]
	v_mfma_f32_16x16x32_bf16 v[18:21], v[166:169], v[190:193], v[18:21]
	v_mfma_f32_16x16x32_bf16 v[2:5], v[166:169], v[206:209], v[2:5]
	v_mfma_f32_16x16x32_bf16 v[6:9], v[158:161], v[206:209], v[6:9]
	s_setprio 0
	s_barrier
	v_add_u32_e32 v141, 0x18000, v139
	ds_read_b128 v[130:133], v141
	ds_read_b128 v[142:145], v141 offset:1024
	ds_read_b128 v[146:149], v141 offset:2048
	ds_read_b128 v[150:153], v141 offset:3072
	v_add_u32_e32 v141, 0x1c000, v139
	ds_read_b128 v[154:157], v141
	ds_read_b128 v[158:161], v141 offset:1024
	ds_read_b128 v[162:165], v141 offset:2048
	ds_read_b128 v[166:169], v141 offset:3072
	s_add_i32 s74, s17, 0x80000
	s_mov_b32 m0, s48
	ds_read_b128 v[170:173], v140 offset:32768
	ds_read_b128 v[174:177], v140 offset:33792
	ds_read_b128 v[178:181], v140 offset:34816
	ds_read_b128 v[182:185], v140 offset:35840
	ds_read_b128 v[186:189], v140 offset:36864
	ds_read_b128 v[190:193], v140 offset:37888
	ds_read_b128 v[200:203], v140 offset:38912
	ds_read_b128 v[206:209], v140 offset:39936
	s_mov_b32 m0, s47
	s_nop 0
	buffer_load_dwordx4 v135, s[4:7], s17 offen lds
	s_mov_b32 m0, s48
	s_nop 0
	buffer_load_dwordx4 v0, s[4:7], s74 offen lds
	s_mov_b32 m0, s49
	s_nop 0
	buffer_load_dwordx4 v135, s[4:7], s74 offen lds
	s_waitcnt vmcnt(8)
	s_waitcnt lgkmcnt(0)
	s_barrier
	s_setprio 1
	v_mfma_f32_16x16x32_bf16 v[126:129], v[130:133], v[170:173], v[126:129]
	v_mfma_f32_16x16x32_bf16 v[122:125], v[146:149], v[170:173], v[122:125]
	v_mfma_f32_16x16x32_bf16 v[106:109], v[146:149], v[178:181], v[106:109]
	v_mfma_f32_16x16x32_bf16 v[110:113], v[130:133], v[178:181], v[110:113]
	v_mfma_f32_16x16x32_bf16 v[94:97], v[130:133], v[186:189], v[94:97]
	v_mfma_f32_16x16x32_bf16 v[90:93], v[146:149], v[186:189], v[90:93]
	v_mfma_f32_16x16x32_bf16 v[74:77], v[146:149], v[200:203], v[74:77]
	v_mfma_f32_16x16x32_bf16 v[78:81], v[130:133], v[200:203], v[78:81]
	v_mfma_f32_16x16x32_bf16 v[126:129], v[142:145], v[174:177], v[126:129]
	v_mfma_f32_16x16x32_bf16 v[122:125], v[150:153], v[174:177], v[122:125]
	v_mfma_f32_16x16x32_bf16 v[106:109], v[150:153], v[182:185], v[106:109]
	v_mfma_f32_16x16x32_bf16 v[110:113], v[142:145], v[182:185], v[110:113]
	v_mfma_f32_16x16x32_bf16 v[94:97], v[142:145], v[190:193], v[94:97]
	v_mfma_f32_16x16x32_bf16 v[90:93], v[150:153], v[190:193], v[90:93]
	v_mfma_f32_16x16x32_bf16 v[74:77], v[150:153], v[206:209], v[74:77]
	v_mfma_f32_16x16x32_bf16 v[78:81], v[142:145], v[206:209], v[78:81]
	v_mfma_f32_16x16x32_bf16 v[118:121], v[154:157], v[170:173], v[118:121]
	v_mfma_f32_16x16x32_bf16 v[114:117], v[162:165], v[170:173], v[114:117]
	v_mfma_f32_16x16x32_bf16 v[98:101], v[162:165], v[178:181], v[98:101]
	v_mfma_f32_16x16x32_bf16 v[102:105], v[154:157], v[178:181], v[102:105]
	v_mfma_f32_16x16x32_bf16 v[86:89], v[154:157], v[186:189], v[86:89]
	v_mfma_f32_16x16x32_bf16 v[82:85], v[162:165], v[186:189], v[82:85]
	v_mfma_f32_16x16x32_bf16 v[66:69], v[162:165], v[200:203], v[66:69]
	v_mfma_f32_16x16x32_bf16 v[70:73], v[154:157], v[200:203], v[70:73]
	v_mfma_f32_16x16x32_bf16 v[118:121], v[158:161], v[174:177], v[118:121]
	v_mfma_f32_16x16x32_bf16 v[114:117], v[166:169], v[174:177], v[114:117]
	v_mfma_f32_16x16x32_bf16 v[98:101], v[166:169], v[182:185], v[98:101]
	v_mfma_f32_16x16x32_bf16 v[102:105], v[158:161], v[182:185], v[102:105]
	v_mfma_f32_16x16x32_bf16 v[86:89], v[158:161], v[190:193], v[86:89]
	v_mfma_f32_16x16x32_bf16 v[82:85], v[166:169], v[190:193], v[82:85]
	v_mfma_f32_16x16x32_bf16 v[66:69], v[166:169], v[206:209], v[66:69]
	v_mfma_f32_16x16x32_bf16 v[70:73], v[158:161], v[206:209], v[70:73]
	s_setprio 0
	s_barrier
; #define PG8_STAGE(bufoff, gbase, voff) do { const int so_ = (int)(unsigned)((const char*)(gbase) - base_##voff); _Pragma("unroll") for (int _i = 0; _i < 2; ++_i) \
;         __builtin_amdgcn_raw_ptr_buffer_load_lds(rs_##voff, (PG8_LAS unsigned*)(lds + (bufoff) + ldsw + _i * 8192), 16, (int)(voff)[_i], so_, 0, 0); } while (0)
; #define PG8_LDA(dst, b, h) do { _Pragma("unroll") for (int m = 0; m < 4; ++m) _Pragma("unroll") for (int k = 0; k < 2; ++k) dst[m][k] = *(const PG8_LAS bf16x8*)(lds + PG8_SA(b, h) + aoff + m * 2048 + k * 1024); } while (0)
; #define PG8_MMA(ai, bj, At, Bt) do { __builtin_amdgcn_s_setprio(1); _Pragma("unroll") for (int m = 0; m < 4; ++m) _Pragma("unroll") for (int n = 0; n < 2; ++n) _Pragma("unroll") for (int k = 0; k < 2; ++k) \
;         acc[ai][bj][m][n] = __builtin_amdgcn_mfma_f32_16x16x32_bf16(Bt[n][k], At[m][k], acc[ai][bj][m][n], 0, 0, 0); __builtin_amdgcn_s_setprio(0); } while (0)
; #define PG8_WAIT_V(n) asm volatile("s_waitcnt vmcnt(" #n ")" ::: "memory")
; #define PG8_WAIT_L(n) asm volatile("s_waitcnt lgkmcnt(" #n ")" ::: "memory")
; #define PG8_BAR __builtin_amdgcn_s_barrier()
; #define PG8_SCHED __builtin_amdgcn_sched_barrier(0)
; template <class Epi, class Sched, bool ALIGN_EPI = false, bool SP2 = false>
; __device__ __forceinline__ void gemm_phase(PG8_LAS unsigned char* lds, const Gemm g, const Sched& S, const Epi& E, int tid_in) {
;     ...
;             PG8_LDA(At, 1, 1); PG8_STAGE(PG8_SB(1, 0), b3, voffB); PG8_STAGE(PG8_SB(1, 1), b3 + hstepB, voffB); PG8_STAGE(PG8_SA(1, 0), a3, voffA);
;             PG8_WAIT_V(8); PG8_WAIT_L(0); PG8_BAR; PG8_MMA(1, 0, At, B0); PG8_MMA(1, 1, At, B1); PG8_BAR; PG8_SCHED;
	s_mov_b32 m0, s53
	s_add_i32 s74, s16, 0x80
	ds_read_b128 v[170:173], v140 offset:49152
	ds_read_b128 v[174:177], v140 offset:50176
	ds_read_b128 v[178:181], v140 offset:51200
	ds_read_b128 v[182:185], v140 offset:52224
	ds_read_b128 v[186:189], v140 offset:53248
	ds_read_b128 v[190:193], v140 offset:54272
	ds_read_b128 v[200:203], v140 offset:55296
	ds_read_b128 v[206:209], v140 offset:56320
	buffer_load_dwordx4 v134, s[40:43], s74 offen lds
	s_mov_b32 m0, s60
	s_add_i32 s16, s16, 0x80080
	buffer_load_dwordx4 v136, s[40:43], s74 offen lds
	s_mov_b32 m0, s63
	s_addk_i32 s17, 0x80
	buffer_load_dwordx4 v134, s[40:43], s16 offen lds
	s_mov_b32 m0, s66
	s_nop 0
	buffer_load_dwordx4 v136, s[40:43], s16 offen lds
	s_mov_b32 m0, s61
	s_nop 0
	buffer_load_dwordx4 v0, s[4:7], s17 offen lds
	s_waitcnt vmcnt(7)
	s_waitcnt lgkmcnt(0)
	s_barrier
	s_setprio 1
	v_mfma_f32_16x16x32_bf16 v[62:65], v[130:133], v[170:173], v[62:65]
	v_mfma_f32_16x16x32_bf16 v[58:61], v[146:149], v[170:173], v[58:61]
	v_mfma_f32_16x16x32_bf16 v[42:45], v[146:149], v[178:181], v[42:45]
	v_mfma_f32_16x16x32_bf16 v[46:49], v[130:133], v[178:181], v[46:49]
	v_mfma_f32_16x16x32_bf16 v[30:33], v[130:133], v[186:189], v[30:33]
	v_mfma_f32_16x16x32_bf16 v[26:29], v[146:149], v[186:189], v[26:29]
	v_mfma_f32_16x16x32_bf16 v[10:13], v[146:149], v[200:203], v[10:13]
	v_mfma_f32_16x16x32_bf16 v[14:17], v[130:133], v[200:203], v[14:17]
	v_mfma_f32_16x16x32_bf16 v[62:65], v[142:145], v[174:177], v[62:65]
	v_mfma_f32_16x16x32_bf16 v[58:61], v[150:153], v[174:177], v[58:61]
	v_mfma_f32_16x16x32_bf16 v[42:45], v[150:153], v[182:185], v[42:45]
	v_mfma_f32_16x16x32_bf16 v[46:49], v[142:145], v[182:185], v[46:49]
	v_mfma_f32_16x16x32_bf16 v[30:33], v[142:145], v[190:193], v[30:33]
	v_mfma_f32_16x16x32_bf16 v[26:29], v[150:153], v[190:193], v[26:29]
	v_mfma_f32_16x16x32_bf16 v[10:13], v[150:153], v[206:209], v[10:13]
	v_mfma_f32_16x16x32_bf16 v[14:17], v[142:145], v[206:209], v[14:17]
	v_mfma_f32_16x16x32_bf16 v[54:57], v[154:157], v[170:173], v[54:57]
	v_mfma_f32_16x16x32_bf16 v[50:53], v[162:165], v[170:173], v[50:53]
	v_mfma_f32_16x16x32_bf16 v[34:37], v[162:165], v[178:181], v[34:37]
	v_mfma_f32_16x16x32_bf16 v[38:41], v[154:157], v[178:181], v[38:41]
	v_mfma_f32_16x16x32_bf16 v[22:25], v[154:157], v[186:189], v[22:25]
	v_mfma_f32_16x16x32_bf16 v[18:21], v[162:165], v[186:189], v[18:21]
	v_mfma_f32_16x16x32_bf16 v[2:5], v[162:165], v[200:203], v[2:5]
	v_mfma_f32_16x16x32_bf16 v[6:9], v[154:157], v[200:203], v[6:9]
	v_mfma_f32_16x16x32_bf16 v[54:57], v[158:161], v[174:177], v[54:57]
	v_mfma_f32_16x16x32_bf16 v[50:53], v[166:169], v[174:177], v[50:53]
	v_mfma_f32_16x16x32_bf16 v[34:37], v[166:169], v[182:185], v[34:37]
	v_mfma_f32_16x16x32_bf16 v[38:41], v[158:161], v[182:185], v[38:41]
	v_mfma_f32_16x16x32_bf16 v[22:25], v[158:161], v[190:193], v[22:25]
	v_mfma_f32_16x16x32_bf16 v[18:21], v[166:169], v[190:193], v[18:21]
	v_mfma_f32_16x16x32_bf16 v[2:5], v[166:169], v[206:209], v[2:5]
	v_mfma_f32_16x16x32_bf16 v[6:9], v[158:161], v[206:209], v[6:9]
	s_setprio 0
	s_barrier
	s_add_i32 s73, s73, 2
	s_add_u32 s19, s19, 0x100
	s_addc_u32 s21, s21, 0
	s_cmp_gt_u32 s73, 29
	s_mov_b64 s[16:17], s[38:39]
